# v32 + out-proj epilogue output section: per-group vmcnt(0) (which also waited for the previous group's store acks) kept only at first use of the gain vectors
# baseline (speedup 1.0000x reference)
.LBB0_722:
	v_mov_b32_e32 v104, v108
	v_mov_b32_e32 v105, v108
	v_pk_mul_f32 v[102:103], v[102:103], v[104:105]
	v_pk_mul_f32 v[100:101], v[100:101], v[108:109]
	v_pk_mul_f32 v[98:99], v[98:99], v[104:105]
	v_pk_mul_f32 v[96:97], v[96:97], v[108:109]
	s_nop 0
	v_pk_mul_f32 v[102:103], v[134:135], v[102:103]
	v_pk_mul_f32 v[100:101], v[132:133], v[100:101]
	v_pk_mul_f32 v[104:105], v[130:131], v[98:99]
	v_pk_mul_f32 v[98:99], v[128:129], v[96:97]
	v_cvt_pk_bf16_f32 v96, v100, v101
	v_cvt_pk_bf16_f32 v97, v102, v103
	v_cvt_pk_bf16_f32 v98, v98, v99
	v_cvt_pk_bf16_f32 v99, v104, v105
	v_lshl_add_u64 v[100:101], v[176:177], 1, s[58:59]
	global_store_dwordx4 v[100:101], v[96:99], off

.LBB0_728:
	v_mov_b32_e32 v88, v96
	v_mov_b32_e32 v89, v96
	v_pk_mul_f32 v[86:87], v[86:87], v[88:89]
	v_pk_mul_f32 v[84:85], v[84:85], v[96:97]
	v_pk_mul_f32 v[82:83], v[82:83], v[88:89]
	v_pk_mul_f32 v[80:81], v[80:81], v[96:97]
	s_nop 0
	v_pk_mul_f32 v[86:87], v[134:135], v[86:87]
	v_pk_mul_f32 v[84:85], v[132:133], v[84:85]
	v_pk_mul_f32 v[88:89], v[130:131], v[82:83]
	v_pk_mul_f32 v[82:83], v[128:129], v[80:81]
	v_cvt_pk_bf16_f32 v80, v84, v85
	v_cvt_pk_bf16_f32 v81, v86, v87
	v_cvt_pk_bf16_f32 v82, v82, v83
	v_cvt_pk_bf16_f32 v83, v88, v89
	v_lshl_add_u64 v[84:85], v[184:185], 1, s[58:59]
	global_store_dwordx4 v[84:85], v[80:83], off

.LBB0_734:
	v_mov_b32_e32 v72, v80
	v_mov_b32_e32 v73, v80
	v_pk_mul_f32 v[70:71], v[70:71], v[72:73]
	v_pk_mul_f32 v[68:69], v[68:69], v[80:81]
	v_pk_mul_f32 v[66:67], v[66:67], v[72:73]
	v_pk_mul_f32 v[64:65], v[64:65], v[80:81]
	s_nop 0
	v_pk_mul_f32 v[70:71], v[134:135], v[70:71]
	v_pk_mul_f32 v[68:69], v[132:133], v[68:69]
	v_pk_mul_f32 v[72:73], v[130:131], v[66:67]
	v_pk_mul_f32 v[66:67], v[128:129], v[64:65]
	v_cvt_pk_bf16_f32 v64, v68, v69
	v_cvt_pk_bf16_f32 v65, v70, v71
	v_cvt_pk_bf16_f32 v66, v66, v67
	v_cvt_pk_bf16_f32 v67, v72, v73
	v_lshl_add_u64 v[68:69], v[192:193], 1, s[58:59]
	global_store_dwordx4 v[68:69], v[64:67], off

.LBB0_740:
	v_mov_b32_e32 v56, v64
	v_mov_b32_e32 v57, v64
	v_pk_mul_f32 v[54:55], v[54:55], v[56:57]
	v_pk_mul_f32 v[52:53], v[52:53], v[64:65]
	v_pk_mul_f32 v[50:51], v[50:51], v[56:57]
	v_pk_mul_f32 v[48:49], v[48:49], v[64:65]
	s_nop 0
	v_pk_mul_f32 v[54:55], v[134:135], v[54:55]
	v_pk_mul_f32 v[52:53], v[132:133], v[52:53]
	v_pk_mul_f32 v[56:57], v[130:131], v[50:51]
	v_pk_mul_f32 v[50:51], v[128:129], v[48:49]
	v_cvt_pk_bf16_f32 v48, v52, v53
	v_cvt_pk_bf16_f32 v49, v54, v55
	v_cvt_pk_bf16_f32 v50, v50, v51
	v_cvt_pk_bf16_f32 v51, v56, v57
	v_lshl_add_u64 v[52:53], v[200:201], 1, s[58:59]
	global_store_dwordx4 v[52:53], v[48:51], off

.LBB0_746:
	v_mov_b32_e32 v40, v48
	v_mov_b32_e32 v41, v48
	v_pk_mul_f32 v[38:39], v[38:39], v[40:41]
	v_pk_mul_f32 v[36:37], v[36:37], v[48:49]
	v_pk_mul_f32 v[34:35], v[34:35], v[40:41]
	v_pk_mul_f32 v[32:33], v[32:33], v[48:49]
	s_nop 0
	v_pk_mul_f32 v[38:39], v[134:135], v[38:39]
	v_pk_mul_f32 v[36:37], v[132:133], v[36:37]
	v_pk_mul_f32 v[40:41], v[130:131], v[34:35]
	v_pk_mul_f32 v[34:35], v[128:129], v[32:33]
	v_cvt_pk_bf16_f32 v32, v36, v37
	v_cvt_pk_bf16_f32 v33, v38, v39
	v_cvt_pk_bf16_f32 v34, v34, v35
	v_cvt_pk_bf16_f32 v35, v40, v41
	v_lshl_add_u64 v[36:37], v[208:209], 1, s[58:59]
	global_store_dwordx4 v[36:37], v[32:35], off

.LBB0_752:
	v_mov_b32_e32 v24, v32
	v_mov_b32_e32 v25, v32
	v_pk_mul_f32 v[22:23], v[22:23], v[24:25]
	v_pk_mul_f32 v[20:21], v[20:21], v[32:33]
	v_pk_mul_f32 v[18:19], v[18:19], v[24:25]
	v_pk_mul_f32 v[16:17], v[16:17], v[32:33]
	s_nop 0
	v_pk_mul_f32 v[22:23], v[134:135], v[22:23]
	v_pk_mul_f32 v[20:21], v[132:133], v[20:21]
	v_pk_mul_f32 v[24:25], v[130:131], v[18:19]
	v_pk_mul_f32 v[18:19], v[128:129], v[16:17]
	v_cvt_pk_bf16_f32 v16, v20, v21
	v_cvt_pk_bf16_f32 v17, v22, v23
	v_cvt_pk_bf16_f32 v18, v18, v19
	v_cvt_pk_bf16_f32 v19, v24, v25
	v_lshl_add_u64 v[20:21], v[216:217], 1, s[58:59]
	global_store_dwordx4 v[20:21], v[16:19], off

.LBB0_758:
	v_mov_b32_e32 v8, v16
	v_mov_b32_e32 v9, v16
	v_pk_mul_f32 v[6:7], v[6:7], v[8:9]
	v_pk_mul_f32 v[4:5], v[4:5], v[16:17]
	v_pk_mul_f32 v[2:3], v[2:3], v[8:9]
	v_pk_mul_f32 v[0:1], v[0:1], v[16:17]
	s_nop 0
	v_pk_mul_f32 v[6:7], v[134:135], v[6:7]
	v_pk_mul_f32 v[4:5], v[132:133], v[4:5]
	v_pk_mul_f32 v[8:9], v[130:131], v[2:3]
	v_pk_mul_f32 v[2:3], v[128:129], v[0:1]
	v_cvt_pk_bf16_f32 v0, v4, v5
	v_cvt_pk_bf16_f32 v1, v6, v7
	v_cvt_pk_bf16_f32 v2, v2, v3
	v_cvt_pk_bf16_f32 v3, v8, v9
	v_lshl_add_u64 v[4:5], v[224:225], 1, s[58:59]
	global_store_dwordx4 v[4:5], v[0:3], off

.LBB0_780:
	v_mov_b32_e32 v110, v108
	v_mov_b32_e32 v111, v108
	v_pk_mul_f32 v[114:115], v[114:115], v[110:111]
	v_pk_mul_f32 v[112:113], v[112:113], v[108:109]
	v_pk_mul_f32 v[106:107], v[106:107], v[110:111]
	v_pk_mul_f32 v[104:105], v[104:105], v[108:109]
	s_nop 0
	v_pk_mul_f32 v[114:115], v[142:143], v[114:115]
	v_pk_mul_f32 v[112:113], v[140:141], v[112:113]
	v_pk_mul_f32 v[110:111], v[138:139], v[106:107]
	v_pk_mul_f32 v[106:107], v[136:137], v[104:105]
	v_cvt_pk_bf16_f32 v104, v112, v113
	v_cvt_pk_bf16_f32 v105, v114, v115
	v_cvt_pk_bf16_f32 v106, v106, v107
	v_cvt_pk_bf16_f32 v107, v110, v111
	v_lshl_add_u64 v[110:111], v[170:171], 1, s[58:59]
	global_store_dwordx4 v[110:111], v[104:107], off
	s_nop 1
	v_cvt_pk_bf16_f32 v104, v100, v101
	v_cvt_pk_bf16_f32 v105, v102, v103
	v_cvt_pk_bf16_f32 v106, v96, v97
	v_cvt_pk_bf16_f32 v107, v98, v99
	global_store_dwordx4 v[180:181], v[104:107], off
	s_cbranch_execnz .LBB0_721

.LBB0_784:
	v_mov_b32_e32 v98, v96
	v_mov_b32_e32 v99, v96
	v_pk_mul_f32 v[94:95], v[94:95], v[98:99]
	v_pk_mul_f32 v[92:93], v[92:93], v[96:97]
	v_pk_mul_f32 v[90:91], v[90:91], v[98:99]
	v_pk_mul_f32 v[88:89], v[88:89], v[96:97]
	s_nop 0
	v_pk_mul_f32 v[94:95], v[142:143], v[94:95]
	v_pk_mul_f32 v[92:93], v[140:141], v[92:93]
	v_pk_mul_f32 v[98:99], v[138:139], v[90:91]
	v_pk_mul_f32 v[90:91], v[136:137], v[88:89]
	v_cvt_pk_bf16_f32 v88, v92, v93
	v_cvt_pk_bf16_f32 v89, v94, v95
	v_cvt_pk_bf16_f32 v90, v90, v91
	v_cvt_pk_bf16_f32 v91, v98, v99
	v_lshl_add_u64 v[92:93], v[182:183], 1, s[58:59]
	global_store_dwordx4 v[92:93], v[88:91], off
	s_nop 1
	v_cvt_pk_bf16_f32 v88, v84, v85
	v_cvt_pk_bf16_f32 v89, v86, v87
	v_cvt_pk_bf16_f32 v90, v80, v81
	v_cvt_pk_bf16_f32 v91, v82, v83
	global_store_dwordx4 v[190:191], v[88:91], off
	s_cbranch_execnz .LBB0_727

.LBB0_788:
	v_mov_b32_e32 v82, v80
	v_mov_b32_e32 v83, v80
	v_pk_mul_f32 v[78:79], v[78:79], v[82:83]
	v_pk_mul_f32 v[76:77], v[76:77], v[80:81]
	v_pk_mul_f32 v[74:75], v[74:75], v[82:83]
	v_pk_mul_f32 v[72:73], v[72:73], v[80:81]
	s_nop 0
	v_pk_mul_f32 v[78:79], v[142:143], v[78:79]
	v_pk_mul_f32 v[76:77], v[140:141], v[76:77]
	v_pk_mul_f32 v[82:83], v[138:139], v[74:75]
	v_pk_mul_f32 v[74:75], v[136:137], v[72:73]
	v_cvt_pk_bf16_f32 v72, v76, v77
	v_cvt_pk_bf16_f32 v73, v78, v79
	v_cvt_pk_bf16_f32 v74, v74, v75
	v_cvt_pk_bf16_f32 v75, v82, v83
	v_lshl_add_u64 v[76:77], v[188:189], 1, s[58:59]
	global_store_dwordx4 v[76:77], v[72:75], off
	s_nop 1
	v_cvt_pk_bf16_f32 v72, v68, v69
	v_cvt_pk_bf16_f32 v73, v70, v71
	v_cvt_pk_bf16_f32 v74, v64, v65
	v_cvt_pk_bf16_f32 v75, v66, v67
	global_store_dwordx4 v[198:199], v[72:75], off
	s_cbranch_execnz .LBB0_733

.LBB0_792:
	v_mov_b32_e32 v66, v64
	v_mov_b32_e32 v67, v64
	v_pk_mul_f32 v[62:63], v[62:63], v[66:67]
	v_pk_mul_f32 v[60:61], v[60:61], v[64:65]
	v_pk_mul_f32 v[58:59], v[58:59], v[66:67]
	v_pk_mul_f32 v[56:57], v[56:57], v[64:65]
	s_nop 0
	v_pk_mul_f32 v[62:63], v[142:143], v[62:63]
	v_pk_mul_f32 v[60:61], v[140:141], v[60:61]
	v_pk_mul_f32 v[66:67], v[138:139], v[58:59]
	v_pk_mul_f32 v[58:59], v[136:137], v[56:57]
	v_cvt_pk_bf16_f32 v56, v60, v61
	v_cvt_pk_bf16_f32 v57, v62, v63
	v_cvt_pk_bf16_f32 v58, v58, v59
	v_cvt_pk_bf16_f32 v59, v66, v67
	v_lshl_add_u64 v[60:61], v[196:197], 1, s[58:59]
	global_store_dwordx4 v[60:61], v[56:59], off
	s_nop 1
	v_cvt_pk_bf16_f32 v56, v52, v53
	v_cvt_pk_bf16_f32 v57, v54, v55
	v_cvt_pk_bf16_f32 v58, v48, v49
	v_cvt_pk_bf16_f32 v59, v50, v51
	global_store_dwordx4 v[206:207], v[56:59], off
	s_cbranch_execnz .LBB0_739

.LBB0_796:
	v_mov_b32_e32 v50, v48
	v_mov_b32_e32 v51, v48
	v_pk_mul_f32 v[46:47], v[46:47], v[50:51]
	v_pk_mul_f32 v[44:45], v[44:45], v[48:49]
	v_pk_mul_f32 v[42:43], v[42:43], v[50:51]
	v_pk_mul_f32 v[40:41], v[40:41], v[48:49]
	s_nop 0
	v_pk_mul_f32 v[46:47], v[142:143], v[46:47]
	v_pk_mul_f32 v[44:45], v[140:141], v[44:45]
	v_pk_mul_f32 v[50:51], v[138:139], v[42:43]
	v_pk_mul_f32 v[42:43], v[136:137], v[40:41]
	v_cvt_pk_bf16_f32 v40, v44, v45
	v_cvt_pk_bf16_f32 v41, v46, v47
	v_cvt_pk_bf16_f32 v42, v42, v43
	v_cvt_pk_bf16_f32 v43, v50, v51
	v_lshl_add_u64 v[44:45], v[204:205], 1, s[58:59]
	global_store_dwordx4 v[44:45], v[40:43], off
	s_nop 1
	v_cvt_pk_bf16_f32 v40, v36, v37
	v_cvt_pk_bf16_f32 v41, v38, v39
	v_cvt_pk_bf16_f32 v42, v32, v33
	v_cvt_pk_bf16_f32 v43, v34, v35
	global_store_dwordx4 v[214:215], v[40:43], off
	s_cbranch_execnz .LBB0_745

.LBB0_800:
	v_mov_b32_e32 v34, v32
	v_mov_b32_e32 v35, v32
	v_pk_mul_f32 v[30:31], v[30:31], v[34:35]
	v_pk_mul_f32 v[28:29], v[28:29], v[32:33]
	v_pk_mul_f32 v[26:27], v[26:27], v[34:35]
	v_pk_mul_f32 v[24:25], v[24:25], v[32:33]
	s_nop 0
	v_pk_mul_f32 v[30:31], v[142:143], v[30:31]
	v_pk_mul_f32 v[28:29], v[140:141], v[28:29]
	v_pk_mul_f32 v[34:35], v[138:139], v[26:27]
	v_pk_mul_f32 v[26:27], v[136:137], v[24:25]
	v_cvt_pk_bf16_f32 v24, v28, v29
	v_cvt_pk_bf16_f32 v25, v30, v31
	v_cvt_pk_bf16_f32 v26, v26, v27
	v_cvt_pk_bf16_f32 v27, v34, v35
	v_lshl_add_u64 v[28:29], v[212:213], 1, s[58:59]
	global_store_dwordx4 v[28:29], v[24:27], off
	s_nop 1
	v_cvt_pk_bf16_f32 v24, v20, v21
	v_cvt_pk_bf16_f32 v25, v22, v23
	v_cvt_pk_bf16_f32 v26, v16, v17
	v_cvt_pk_bf16_f32 v27, v18, v19
	global_store_dwordx4 v[222:223], v[24:27], off
	s_cbranch_execnz .LBB0_751

.LBB0_804:
	v_mov_b32_e32 v18, v16
	v_mov_b32_e32 v19, v16
	v_pk_mul_f32 v[14:15], v[14:15], v[18:19]
	v_pk_mul_f32 v[12:13], v[12:13], v[16:17]
	v_pk_mul_f32 v[10:11], v[10:11], v[18:19]
	v_pk_mul_f32 v[8:9], v[8:9], v[16:17]
	s_nop 0
	v_pk_mul_f32 v[14:15], v[142:143], v[14:15]
	v_pk_mul_f32 v[12:13], v[140:141], v[12:13]
	v_pk_mul_f32 v[18:19], v[138:139], v[10:11]
	v_pk_mul_f32 v[10:11], v[136:137], v[8:9]
	v_cvt_pk_bf16_f32 v8, v12, v13
	v_cvt_pk_bf16_f32 v9, v14, v15
	v_cvt_pk_bf16_f32 v10, v10, v11
	v_cvt_pk_bf16_f32 v11, v18, v19
	v_lshl_add_u64 v[12:13], v[220:221], 1, s[58:59]
	global_store_dwordx4 v[12:13], v[8:11], off
	s_nop 1
	v_cvt_pk_bf16_f32 v8, v4, v5
	v_cvt_pk_bf16_f32 v9, v6, v7
	v_cvt_pk_bf16_f32 v10, v0, v1
	v_cvt_pk_bf16_f32 v11, v2, v3
	global_store_dwordx4 v[228:229], v[8:11], off
	s_cbranch_execnz .LBB0_757
